# HGRN2 prompt pass: dead denormal/inf handling removed from the 16 per-chunk log expansions (inputs clamped to >= 2^-10, bitwise identical); on top of v9
# speedup vs baseline: 1.0029x; 1.0029x over previous
.LBB0_1410:
	s_waitcnt vmcnt(22)
	v_lshlrev_b32_e32 v101, 16, v16
	v_sub_f32_e32 v58, 1.0, v101
	v_max_f32_e32 v58, 0x3a800000, v58
	s_mov_b32 s2, 0x800000
	s_mov_b32 s3, 0x3f317217
	s_mov_b32 s28, 0x7f800000
	v_log_f32_e32 v58, v58
	v_and_b32_e32 v104, 0xffff0000, v16
	s_waitcnt vmcnt(20)
	v_lshlrev_b32_e32 v102, 16, v17
	v_and_b32_e32 v105, 0xffff0000, v17
	v_mul_f32_e32 v59, 0x3f317217, v58
	v_fma_f32 v59, v58, s3, -v59
	v_fmac_f32_e32 v59, 0x3377d1cf, v58
	v_fmac_f32_e32 v59, 0x3f317217, v58
	s_waitcnt vmcnt(16)
	v_lshlrev_b32_e32 v103, 16, v18
	v_and_b32_e32 v107, 0xffff0000, v18
	v_mov_b32_e32 v58, v59

	v_sub_f32_e32 v59, 1.0, v104
	v_max_f32_e32 v59, 0x3a800000, v59
	s_waitcnt vmcnt(14)
	v_lshlrev_b32_e32 v106, 16, v19
	v_and_b32_e32 v109, 0xffff0000, v19
	v_log_f32_e32 v59, v59
	s_waitcnt vmcnt(10)
	v_lshlrev_b32_e32 v108, 16, v20
	v_and_b32_e32 v112, 0xffff0000, v20
	s_waitcnt vmcnt(8)
	v_lshlrev_b32_e32 v110, 16, v21
	v_mul_f32_e32 v60, 0x3f317217, v59
	v_fma_f32 v60, v59, s3, -v60
	v_fmac_f32_e32 v60, 0x3377d1cf, v59
	v_fmac_f32_e32 v60, 0x3f317217, v59
	v_and_b32_e32 v114, 0xffff0000, v21
	s_waitcnt vmcnt(3)
	v_lshlrev_b32_e32 v113, 16, v22
	v_mov_b32_e32 v59, v60

	v_pk_add_f32 v[62:63], v[58:59], 0 op_sel_hi:[1,0]
	v_sub_f32_e32 v58, 1.0, v102
	v_max_f32_e32 v58, 0x3a800000, v58
	v_and_b32_e32 v116, 0xffff0000, v22
	s_waitcnt vmcnt(2)
	v_lshlrev_b32_e32 v115, 16, v23
	v_log_f32_e32 v58, v58
	v_and_b32_e32 v117, 0xffff0000, v23
	v_mov_b32_e32 v99, v83
	v_mov_b32_e32 v0, v82
	v_mul_f32_e32 v59, 0x3f317217, v58
	v_fma_f32 v59, v58, s3, -v59
	v_fmac_f32_e32 v59, 0x3377d1cf, v58
	v_fmac_f32_e32 v59, 0x3f317217, v58
	v_mov_b32_e32 v100, v98

	v_mov_b32_e32 v58, v59

	v_sub_f32_e32 v59, 1.0, v105
	v_max_f32_e32 v59, 0x3a800000, v59

	v_log_f32_e32 v59, v59
	s_nop 0
	v_mul_f32_e32 v60, 0x3f317217, v59
	v_fma_f32 v60, v59, s3, -v60
	v_fmac_f32_e32 v60, 0x3377d1cf, v59
	v_fmac_f32_e32 v60, 0x3f317217, v59

	v_mov_b32_e32 v59, v60

	v_sub_f32_e32 v60, 1.0, v103
	v_max_f32_e32 v60, 0x3a800000, v60
	v_pk_add_f32 v[58:59], v[58:59], v[62:63]

	v_log_f32_e32 v60, v60
	s_nop 0
	v_mul_f32_e32 v61, 0x3f317217, v60
	v_fma_f32 v61, v60, s3, -v61
	v_fmac_f32_e32 v61, 0x3377d1cf, v60
	v_fmac_f32_e32 v61, 0x3f317217, v60

	v_mov_b32_e32 v60, v61

	v_sub_f32_e32 v61, 1.0, v107
	v_max_f32_e32 v61, 0x3a800000, v61

	v_log_f32_e32 v61, v61
	s_nop 0
	v_mul_f32_e32 v64, 0x3f317217, v61
	v_fma_f32 v64, v61, s3, -v64
	v_fmac_f32_e32 v64, 0x3377d1cf, v61
	v_fmac_f32_e32 v64, 0x3f317217, v61
	s_nop 1
	v_mov_b32_e32 v61, v64

	v_sub_f32_e32 v64, 1.0, v106
	v_max_f32_e32 v64, 0x3a800000, v64
	v_pk_add_f32 v[60:61], v[60:61], v[58:59]

	v_log_f32_e32 v64, v64
	s_nop 0
	v_mul_f32_e32 v65, 0x3f317217, v64
	v_fma_f32 v65, v64, s3, -v65
	v_fmac_f32_e32 v65, 0x3377d1cf, v64
	v_fmac_f32_e32 v65, 0x3f317217, v64
	s_nop 1
	v_mov_b32_e32 v64, v65

	v_sub_f32_e32 v65, 1.0, v109
	v_max_f32_e32 v65, 0x3a800000, v65

	v_log_f32_e32 v65, v65
	s_nop 0
	v_mul_f32_e32 v66, 0x3f317217, v65
	v_fma_f32 v66, v65, s3, -v66
	v_fmac_f32_e32 v66, 0x3377d1cf, v65
	v_fmac_f32_e32 v66, 0x3f317217, v65
	s_nop 1
	v_mov_b32_e32 v65, v66

	v_pk_add_f32 v[66:67], v[64:65], v[60:61]
	v_sub_f32_e32 v64, 1.0, v108
	v_max_f32_e32 v64, 0x3a800000, v64

	v_log_f32_e32 v64, v64
	s_nop 0
	v_mul_f32_e32 v65, 0x3f317217, v64
	v_fma_f32 v65, v64, s3, -v65
	v_fmac_f32_e32 v65, 0x3377d1cf, v64
	v_fmac_f32_e32 v65, 0x3f317217, v64
	s_nop 1
	v_mov_b32_e32 v64, v65

	v_sub_f32_e32 v65, 1.0, v112
	v_max_f32_e32 v65, 0x3a800000, v65

	v_log_f32_e32 v65, v65
	s_nop 0
	v_mul_f32_e32 v68, 0x3f317217, v65
	v_fma_f32 v68, v65, s3, -v68
	v_fmac_f32_e32 v68, 0x3377d1cf, v65
	v_fmac_f32_e32 v68, 0x3f317217, v65
	s_nop 1
	v_mov_b32_e32 v65, v68

	v_pk_add_f32 v[68:69], v[64:65], v[66:67]
	v_sub_f32_e32 v64, 1.0, v110
	v_max_f32_e32 v64, 0x3a800000, v64

	v_log_f32_e32 v64, v64
	s_nop 0
	v_mul_f32_e32 v65, 0x3f317217, v64
	v_fma_f32 v65, v64, s3, -v65
	v_fmac_f32_e32 v65, 0x3377d1cf, v64
	v_fmac_f32_e32 v65, 0x3f317217, v64
	s_nop 1
	v_mov_b32_e32 v64, v65

	v_sub_f32_e32 v65, 1.0, v114
	v_max_f32_e32 v65, 0x3a800000, v65

	v_log_f32_e32 v65, v65
	s_nop 0
	v_mul_f32_e32 v70, 0x3f317217, v65
	v_fma_f32 v70, v65, s3, -v70
	v_fmac_f32_e32 v70, 0x3377d1cf, v65
	v_fmac_f32_e32 v70, 0x3f317217, v65
	s_nop 1
	v_mov_b32_e32 v65, v70

	v_pk_add_f32 v[70:71], v[64:65], v[68:69]
	v_sub_f32_e32 v64, 1.0, v113
	v_max_f32_e32 v64, 0x3a800000, v64

	v_log_f32_e32 v64, v64
	s_nop 0
	v_mul_f32_e32 v65, 0x3f317217, v64
	v_fma_f32 v65, v64, s3, -v65
	v_fmac_f32_e32 v65, 0x3377d1cf, v64
	v_fmac_f32_e32 v65, 0x3f317217, v64
	s_nop 1
	v_mov_b32_e32 v64, v65

	v_sub_f32_e32 v65, 1.0, v116
	v_max_f32_e32 v65, 0x3a800000, v65

	v_log_f32_e32 v65, v65
	s_nop 0
	v_mul_f32_e32 v72, 0x3f317217, v65
	v_fma_f32 v72, v65, s3, -v72
	v_fmac_f32_e32 v72, 0x3377d1cf, v65
	v_fmac_f32_e32 v72, 0x3f317217, v65
	s_nop 1
	v_mov_b32_e32 v65, v72

	v_pk_add_f32 v[72:73], v[64:65], v[70:71]
	v_sub_f32_e32 v64, 1.0, v115
	v_max_f32_e32 v64, 0x3a800000, v64

	v_log_f32_e32 v64, v64
	s_nop 0
	v_mul_f32_e32 v65, 0x3f317217, v64
	v_fma_f32 v65, v64, s3, -v65
	v_fmac_f32_e32 v65, 0x3377d1cf, v64
	v_fmac_f32_e32 v65, 0x3f317217, v64
	s_nop 1
	v_mov_b32_e32 v64, v65

	v_sub_f32_e32 v65, 1.0, v117
	v_max_f32_e32 v65, 0x3a800000, v65

	v_log_f32_e32 v65, v65
	s_nop 0
	v_mul_f32_e32 v74, 0x3f317217, v65
	v_fma_f32 v74, v65, s3, -v74
	v_fmac_f32_e32 v74, 0x3377d1cf, v65
	v_fmac_f32_e32 v74, 0x3f317217, v65
	s_nop 1
	v_mov_b32_e32 v65, v74

	v_pk_add_f32 v[74:75], v[64:65], v[72:73]
	v_lshlrev_b32_e32 v64, 2, v0
	v_add_u32_e32 v65, s76, v64
	ds_write_b64 v65, v[74:75]
	s_waitcnt lgkmcnt(0)
	s_barrier
	v_add_u32_e32 v111, 0, v64
	ds_read2st64_b64 v[76:79], v111 offset1:1
	s_andn2_b64 vcc, exec, s[58:59]
	s_waitcnt lgkmcnt(0)
	v_pk_add_f32 v[64:65], v[76:77], 0 op_sel_hi:[1,0]
	s_nop 0
	v_pk_add_f32 v[80:81], v[64:65], v[78:79]
	ds_read2st64_b64 v[76:79], v111 offset0:2 offset1:3
	v_cndmask_b32_e64 v86, 0, v65, s[10:11]
	v_cndmask_b32_e64 v87, 0, v64, s[10:11]
	s_waitcnt lgkmcnt(0)
	v_pk_add_f32 v[64:65], v[80:81], v[76:77]
	v_cndmask_b32_e64 v76, v87, v80, s[12:13]
	v_cndmask_b32_e64 v77, v86, v81, s[12:13]
	v_cndmask_b32_e64 v86, v77, v65, s[14:15]
	v_cndmask_b32_e64 v87, v76, v64, s[14:15]
	v_pk_add_f32 v[94:95], v[64:65], v[78:79]
	ds_read2st64_b64 v[76:79], v111 offset0:4 offset1:5
	s_waitcnt lgkmcnt(0)
	v_pk_add_f32 v[64:65], v[94:95], v[76:77]
	v_cndmask_b32_e64 v76, v87, v94, s[16:17]
	v_cndmask_b32_e64 v77, v86, v95, s[16:17]
	v_cndmask_b32_e64 v77, v77, v65, s[18:19]
	v_cndmask_b32_e64 v76, v76, v64, s[18:19]
	v_pk_add_f32 v[96:97], v[64:65], v[78:79]
	s_nop 0
	v_cndmask_b32_e64 v88, v76, v96, s[20:21]
	v_cndmask_b32_e64 v89, v77, v97, s[20:21]
	ds_read2st64_b64 v[76:79], v111 offset0:6 offset1:7
	s_waitcnt lgkmcnt(0)
	v_pk_add_f32 v[86:87], v[96:97], v[76:77]
	s_nop 0
	v_pk_add_f32 v[64:65], v[86:87], v[78:79]
	v_cndmask_b32_e64 v76, 0, v81, s[8:9]
	v_cndmask_b32_e64 v77, 0, v80, s[8:9]
	v_cndmask_b32_e64 v78, v81, v95, s[8:9]
	v_cndmask_b32_e64 v79, v80, v94, s[8:9]
	v_cndmask_b32_e64 v77, v77, v94, s[6:7]
	v_cndmask_b32_e64 v76, v76, v95, s[6:7]
	v_cndmask_b32_e64 v79, v79, v96, s[6:7]
	v_cndmask_b32_e64 v78, v78, v97, s[6:7]
	v_cndmask_b32_e64 v91, v76, v97, s[24:25]
	v_cndmask_b32_e64 v90, v77, v96, s[24:25]
	v_cndmask_b32_e64 v77, v78, v65, s[24:25]
	v_cndmask_b32_e64 v76, v79, v64, s[24:25]
	v_pk_add_f32 v[78:79], v[80:81], v[76:77] neg_lo:[0,1] neg_hi:[0,1]
	v_mul_f32_e32 v92, 0x3fb8aa3b, v90
	v_min_f32_e32 v78, 0, v78
	v_mul_f32_e32 v78, 0x3fb8aa3b, v78
	v_exp_f32_e32 v118, v78
	v_min_f32_e32 v78, 0, v79
	v_mul_f32_e32 v78, 0x3fb8aa3b, v78
	v_exp_f32_e32 v119, v78
	v_cndmask_b32_e64 v79, v89, v87, s[22:23]
	v_cndmask_b32_e64 v78, v88, v86, s[22:23]
	v_pk_add_f32 v[88:89], v[78:79], v[90:91] neg_lo:[0,1] neg_hi:[0,1]
	v_mul_f32_e32 v93, 0x3fb8aa3b, v91
	v_pk_add_f32 v[62:63], v[62:63], v[88:89]
	v_pk_add_f32 v[86:87], v[76:77], v[90:91] neg_lo:[0,1] neg_hi:[0,1]
	v_mul_f32_e32 v90, 0x3fb8aa3b, v62
	v_exp_f32_e32 v78, v93
	v_exp_f32_e32 v93, v90
	v_mul_f32_e32 v90, 0x3fb8aa3b, v63
	v_exp_f32_e32 v123, v90
	v_mul_f32_e32 v79, 0x3fb8aa3b, v84
	v_rcp_f32_e32 v90, v93
	v_exp_f32_e32 v80, v92
	v_exp_f32_e32 v92, v79
	v_mul_f32_e32 v79, 0x3fb8aa3b, v85
	v_exp_f32_e32 v122, v79
	v_min_f32_e32 v121, 0x79297b5a, v90
	v_rcp_f32_e32 v90, v123
	v_pk_add_f32 v[62:63], v[86:87], v[62:63] neg_lo:[0,1] neg_hi:[0,1]
	v_lshlrev_b32_e32 v79, 1, v0
	v_mul_f32_e32 v62, 0x3fb8aa3b, v62
	v_sub_u32_e32 v120, v111, v79
	v_lshlrev_b32_e32 v81, 16, v8
	v_and_b32_e32 v79, 0xffff0000, v8
	v_exp_f32_e32 v125, v62
	v_mul_f32_e32 v62, 0x3fb8aa3b, v63
	v_min_f32_e32 v124, 0x79297b5a, v90
	v_exp_f32_e32 v126, v62
	v_pk_mul_f32 v[90:91], v[92:93], v[80:81]
	v_pk_mul_f32 v[92:93], v[122:123], v[78:79]
	v_lshl_add_u32 v63, s39, 1, v120
	v_cvt_pk_bf16_f32 v62, v91, v93
	ds_write_b32 v63, v62 offset:8192
	v_mul_f32_e32 v62, v80, v91
	v_mul_f32_e32 v79, v78, v93
	v_cvt_pk_bf16_f32 v62, v62, v79
	ds_write_b32 v63, v62 offset:25600
	v_mul_f32_e32 v62, v90, v91
	v_mul_f32_e32 v63, v92, v93
	v_cvt_pk_bf16_f32 v79, v62, v63
	v_lshl_add_u64 v[62:63], v[0:1], 1, s[34:35]
	v_lshl_add_u64 v[122:123], s[52:53], 0, v[62:63]
	v_mul_f32_e32 v91, v121, v101
	v_mul_f32_e32 v93, v124, v104
	global_store_dword v[122:123], v79, off
	v_cvt_pk_bf16_f32 v91, v91, v93
	v_add_u32_e32 v93, s38, v120
	ds_write_b32 v93, v91 offset:43008
	v_cndmask_b32_e64 v91, 0, 1, s[58:59]
	v_mul_f32_e32 v79, v125, v101
	v_mul_f32_e32 v81, v126, v104
	v_cmp_ne_u32_e64 s[26:27], 1, v91
	v_add_u32_e32 v101, s33, v120
	s_cbranch_vccnz .LBB0_1412
	v_mul_f32_e32 v91, v119, v81
	v_mul_f32_e32 v93, v118, v79
	v_cvt_pk_bf16_f32 v91, v93, v91
	ds_write_b32 v101, v91 offset:47360
